# gating (SGU) units run in the idle tail of the input-projection phase on the workgroups that produced the g tiles (VG tile assignment re-mapped so g tiles sit on 2-tile workgroups); mixer phase is att
# speedup vs baseline: 1.0074x; 1.0042x over previous
; #define LAS __attribute__((address_space(3)))
; __device__ __forceinline__ float fx_get(const i64* p) { return (float)(*p) * FXI; }
; #define WSBASE() GAS unsigned char* wsg_ = (GAS unsigned char*)a.ws; asm volatile("" : "+s"(wsg_)); unsigned char* ws = (unsigned char*)wsg_; i64* stats = (i64*)(ws + WS_STATS); i64* st = stats + (size_t)(6 * l) * MTOK; unsigned char* wl = ws + WS_W + (size_t)l * WL_STRIDE; (void)st; (void)wl
; template <bool BY_COL, class Sched> __device__ __forceinline__ void stage_rstd(LAS unsigned char* lds, const Sched& S, const i64* ssq) {
;     LAS float* rsl = (LAS float*)(lds + RSL_OFF); const int tid = threadIdx.x;
; #pragma unroll 1
;     for (int i = 0; i < RSL_UNITS; ++i) { Unit u; if (!S.next(i, u)) break;
;         if (tid < 256) rsl[i * 256 + tid] = __builtin_amdgcn_rsqf(fx_get(ssq + (BY_COL ? u.pn : u.pm) * 256 + tid) * (1.0f / DM) + EPS); }
;     __syncthreads();
; __global__ void __launch_bounds__(NWAVES * 64, 2) fwd_kernel(Args a) {
;     ...
;                 { WSBASE();
;                   pg8::Gemm g{(const bf16_t*)(ws + WS_XB), (const bf16_t*)(wl + WL_INN), MTOK, 1536, DM}; typedef pg8::StaticOrderT<MTOK, 1536> SchedT; SchedT S; S.init(G, cu);
;                   stage_rstd<false>(lds, S, st + 1 * MTOK);
;                   EpiQKU E{(bf16_t*)(ws + WS_Q), (const LAS float*)(lds + RSL_OFF), (const float*)(ws + WS_ROT), (const float*)(ws + WS_ROT) + SEQ * 8};
;                   pg8::gemm_phase<EpiQKU, SchedT, true>(lds, g, S, E);
;                   if (DUP & 16) pg8::gemm_phase<EpiQKU, SchedT, true>(lds, g, S, E); }
;                 { WSBASE();
;                   pg8::Gemm g{(const bf16_t*)(wl + WL_INS), (const bf16_t*)(ws + WS_XB), 1024, MTOK, DM}; typedef pg8::StaticOrderT<1024, MTOK> SchedT; SchedT S; S.init(G, cu);
;                   stage_rstd<true>(lds, S, st + 1 * MTOK);
;                   EpiVG E{(bf16_t*)(ws + WS_VT1), (bf16_t*)(ws + WS_VT4), (bf16_t*)(ws + WS_VT16), (bf16_t*)(ws + WS_GT), (const LAS float*)(lds + RSL_OFF), st + 3 * MTOK, st + 4 * MTOK};
;                   pg8::gemm_phase<EpiVG, SchedT, true>(lds, g, S, E);
.LBB0_819:
	s_load_dwordx2 s[94:95], s[0:1], 0xa0
	s_waitcnt vmcnt(0)
	s_barrier
	s_cmp_ge_u32 s2, 0x80
	s_cbranch_scc1 .Ls1_done
	s_mov_b64 s[4:5], exec
	v_readlane_b32 s6, v254, 7
	v_readlane_b32 s7, v254, 8
	s_nop 1
	s_and_b64 exec, s[4:5], s[6:7]
	s_cbranch_execz .Ls1_skip
	v_readlane_b32 s6, v252, 34
	v_readlane_b32 s7, v252, 35
	s_and_b32 s8, s2, 7
	s_lshl_b32 s8, s8, 3
	s_bfe_u32 s9, s2, 0x30003
	s_or_b32 s8, s8, s9
	s_lshl_b32 s8, s8, 5
	s_addk_i32 s8, 0x3610
	s_add_u32 s6, s6, s8
	s_addc_u32 s7, s7, 0
	v_mov_b32_e32 v2, 0
	v_mov_b32_e32 v3, 1
	s_nop 1
	global_atomic_add v2, v3, s[6:7]
.Ls1_skip:
	s_mov_b64 exec, s[4:5]
.Ls1_done:
.LBB0_820:
	s_waitcnt lgkmcnt(0)
	s_mov_b64 s[44:45], s[94:95]
	s_add_u32 s30, s44, s90
	s_addc_u32 s31, s45, s91
	v_mov_b32_e32 v215, v1
	v_lshl_add_u64 v[2:3], s[30:31], 0, v[214:215]
	s_mov_b64 s[4:5], 0x20000
	v_lshl_add_u64 v[2:3], v[2:3], 0, s[4:5]
	s_movk_i32 s4, 0xe800
	s_mov_b64 s[28:29], s[2:3]
	s_cmpk_lg_i32 s70, 0x100
	s_cbranch_scc1 .Lvg_remap_done
	s_lshr_b32 s5, s2, 3
	s_lshr_b32 s6, s5, 4
	s_lshl_b32 s6, s6, 1
	s_and_b32 s7, s5, 1
	s_or_b32 s6, s6, s7
	s_bfe_u32 s5, s5, 0x30001
	v_writelane_b32 v254, s6, 15
	s_lshl_b32 s7, s6, 19
	v_writelane_b32 v254, s7, 17
	s_lshl_b32 s28, s5, 2
	s_add_i32 s28, s28, s6
	s_lshl_b32 s28, s28, 3
	s_and_b32 s7, s2, 7
	s_or_b32 s28, s28, s7
	s_lshl_b32 s7, s7, 3
	s_or_b32 s7, s7, s5
	v_writelane_b32 v253, s7, 58
	s_lshl_b32 s7, s7, 19
	v_writelane_b32 v253, s7, 59
	s_mov_b32 s7, 0
	v_writelane_b32 v253, s7, 60
	v_writelane_b32 v254, s7, 16
	v_writelane_b32 v254, s7, 18
.Lvg_remap_done:
	s_branch .LBB0_823
.LBB0_821:
	s_or_b64 exec, exec, s[42:43]
	s_addk_i32 s4, 0x400
	s_add_u32 s28, s28, s70
	s_addc_u32 s29, s29, s61
	s_cmp_eq_u32 s4, 0
	s_cselect_b64 s[42:43], -1, 0

; #define PG8_WAIT_V(n) asm volatile("s_waitcnt vmcnt(" #n ")" ::: "memory")
; #define PG8_BAR __builtin_amdgcn_s_barrier()
; template <class Epi, class Sched, bool ALIGN_EPI = false>
; __device__ __forceinline__ void gemm_phase(PG8_LAS unsigned char* lds, const Gemm g, const Sched& S, const Epi& E) {
;     ...
;     PG8_WAIT_V(0);
;     if constexpr (!ALIGN_EPI) { if (wr == 0) PG8_BAR; }
;     PG8_BAR;
; __global__ void __launch_bounds__(NWAVES * 64, 2) fwd_kernel(Args a) {
;     ...
;                   pg8::gemm_phase<EpiVG, SchedT, true>(lds, g, S, E);
.LBB0_873:
	s_load_dwordx2 s[94:95], s[0:1], 0xa0
	s_waitcnt vmcnt(0)
	s_barrier
	s_cmp_lt_u32 s2, 0x80
	s_cbranch_scc1 .Ls2_done
	s_mov_b64 s[4:5], exec
	v_readlane_b32 s6, v254, 7
	v_readlane_b32 s7, v254, 8
	s_nop 1
	s_and_b64 exec, s[4:5], s[6:7]
	s_cbranch_execz .Ls2_skip
	v_readlane_b32 s6, v252, 34
	v_readlane_b32 s7, v252, 35
	s_and_b32 s8, s2, 7
	s_lshl_b32 s8, s8, 3
	s_bfe_u32 s9, s2, 0x30004
	s_or_b32 s8, s8, s9
	s_lshl_b32 s8, s8, 5
	s_addk_i32 s8, 0x3610
	s_add_u32 s6, s6, s8
	s_addc_u32 s7, s7, 0
	v_mov_b32_e32 v2, 0
	v_mov_b32_e32 v3, 1
	s_nop 1
	global_atomic_add v2, v3, s[6:7]

.Ls2_done:
.LBB0_874:
	v_readlane_b32 s4, v253, 6
	v_readlane_b32 s5, v253, 7
	s_andn2_b64 vcc, exec, s[4:5]
	s_cbranch_vccnz .LBB0_1022
	v_mov_b32_e32 v0, v210
	s_mov_b64 s[28:29], -1
	v_readfirstlane_b32 s4, v0
	v_and_b32_e32 v141, 63, v0
	s_ashr_i32 s7, s4, 6
	v_readlane_b32 s4, v253, 8
	v_lshlrev_b32_e32 v2, 2, v141
	s_add_i32 s4, s7, s4
	s_cmpk_lt_i32 s4, 0x100
	v_lshrrev_b32_e32 v130, 4, v141
	v_and_b32_e32 v132, 60, v2
	s_movk_i32 s19, 0xb00
	s_cbranch_scc1 .LBB0_877
	v_lshrrev_b32_e32 v0, 4, v141
	v_and_b32_e32 v66, 60, v2
	v_mov_b32_e32 v67, v1
	s_mov_b64 s[28:29], 0
	v_mov_b64_e32 v[134:135], v[66:67]
	v_mov_b64_e32 v[136:137], v[0:1]

; __device__ __forceinline__ unsigned xb_ld(unsigned* p)              { return __hip_atomic_load(p, __ATOMIC_RELAXED, __HIP_MEMORY_SCOPE_AGENT); }
; __device__ __forceinline__ unsigned xb_add(unsigned* p, unsigned v) { return __hip_atomic_fetch_add(p, v, __ATOMIC_RELAXED, __HIP_MEMORY_SCOPE_AGENT); }
; #define XB_SPIN(cond, bar) do { unsigned _sp = 0; while (cond) { __builtin_amdgcn_s_sleep(8); \
;     if ((++_sp & 255u) == 0u) { if (xb_ld(&(bar)[XB_TMO])) break; if (_sp > XB_SPIN_CAP) { atomicAdd(&(bar)[XB_TMO], 1u); break; } } } } while (0)
; #define SEAM(k) do { if ((k) + 1 < hi) { if ((k) == 0) grid.sync(); else { xcd_barrier(bar); if (DUP & 4) xcd_barrier(bar); } } } while (0)
; #define SEAM(k) do { } while (0)
; __device__ __forceinline__ void xcd_barrier(const XcdBarrier& b) {
;     asm volatile("s_waitcnt vmcnt(0)" ::: "memory");
;     __syncthreads();
;     if (threadIdx.x == 0) {
;         unsigned* bar = b.bar;
;         __builtin_amdgcn_s_waitcnt(0);
;         unsigned nloc = b.st[0], nx = b.st[1];
;         if (nloc == 0u) { xcd_barrier_complete(bar, b.x, nloc, nx); b.st[0] = nloc; b.st[1] = nx; }
;         const unsigned old = xb_add(&bar[XB_XSUB(b.x)], 1u);
;         const unsigned gen = old / nloc;
;         if (old + 1u == (gen + 1u) * nloc) {
;             __builtin_amdgcn_fence(__ATOMIC_RELEASE, "agent");
;             asm volatile("s_waitcnt vmcnt(0)" ::: "memory");
;             const unsigned og = xb_add(&bar[XB_TOP], 1u);
;             const unsigned tg = og / nx;
;             if (og + 1u == (tg + 1u) * nx) xb_add(&bar[XB_TOPGEN], 1u);
;             else XB_SPIN(xb_ld(&bar[XB_TOPGEN]) == tg, bar);
;             __builtin_amdgcn_fence(__ATOMIC_ACQUIRE, "agent");
;             xb_add(&bar[XB_XGEN(b.x)], 1u);
;             asm volatile("s_waitcnt vmcnt(0)" ::: "memory");
;         } else {
;             XB_SPIN(xb_ld(&bar[XB_XGEN(b.x)]) == gen, bar);
;             __builtin_amdgcn_fence(__ATOMIC_ACQUIRE, "agent");
;             asm volatile("s_waitcnt vmcnt(0)" ::: "memory");
;         }
;     }
;     __syncthreads();
; }
; __global__ void __launch_bounds__(NWAVES * 64, 2) fwd_kernel(Args a) {
;     ...
;                 IDLE_CONVERT(1);
;                 SEAM(pb + 2);
.LBB0_1022:
	v_readlane_b32 s4, v254, 52
	v_readlane_b32 s5, v254, 53
	s_andn2_b64 vcc, exec, s[4:5]
	s_cbranch_vccnz .LBB0_1077
	s_cmp_lt_u32 s2, 0x80
	s_cbranch_scc1 .Lin_seam
	v_mov_b32_e32 v0, 0x23084
	ds_read_b32 v0, v0
	s_waitcnt lgkmcnt(0)
	v_readfirstlane_b32 s4, v0
	s_nop 3
	s_cmp_eq_u32 s4, 0
	s_cbranch_scc1 .Lin_seam
	s_waitcnt vmcnt(0)
	s_mov_b64 s[4:5], exec
	v_readlane_b32 s6, v254, 7
	v_readlane_b32 s7, v254, 8
	s_nop 1
	s_and_b64 exec, s[4:5], s[6:7]
	s_cbranch_execz .Les_polled
	v_readlane_b32 s6, v252, 34
	v_readlane_b32 s7, v252, 35
	s_and_b32 s8, s2, 7
	s_lshl_b32 s8, s8, 3
	s_bfe_u32 s9, s2, 0x30004
	s_or_b32 s8, s8, s9
	s_lshl_b32 s8, s8, 5
	s_addk_i32 s8, 0x3610
	s_add_u32 s6, s6, s8
	s_addc_u32 s7, s7, 0
	v_mov_b32_e32 v2, 0x230a4
	v_mov_b32_e32 v3, 4
	ds_add_rtn_u32 v5, v2, v3
	v_mov_b32_e32 v2, 0
	s_waitcnt lgkmcnt(0)
	v_add_u32_e32 v5, 4, v5
	s_mov_b32 s8, 0
.Les_poll:
	global_load_dword v3, v2, s[6:7] sc1
	s_waitcnt vmcnt(0)
	v_cmp_ge_u32_e32 vcc, v3, v5
	s_cbranch_vccnz .Les_polled
	s_add_i32 s8, s8, 1
	s_cmp_lt_u32 s8, 0x2000
	s_cbranch_scc0 .Les_polled
	s_sleep 2
	s_branch .Les_poll
.Les_polled:
	s_mov_b64 exec, s[4:5]
	s_barrier
	buffer_inv sc1
	v_writelane_b32 v255, s46, 10
	v_writelane_b32 v255, s47, 11
	v_writelane_b32 v255, s48, 12
	v_writelane_b32 v255, s49, 13
	v_writelane_b32 v255, s50, 14
	v_writelane_b32 v255, s51, 15
	v_writelane_b32 v255, s52, 16
	v_writelane_b32 v255, s53, 17
	s_branch .Lsgu_early
.Lin_seam:
	s_waitcnt vmcnt(0)
	s_waitcnt vmcnt(0) lgkmcnt(0)
	s_barrier
	s_mov_b64 s[28:29], exec
	v_readlane_b32 s4, v254, 7
	v_readlane_b32 s5, v254, 8
	s_and_b64 s[4:5], s[28:29], s[4:5]
	s_mov_b64 exec, s[4:5]
	s_cbranch_execz .LBB0_1076
	v_readlane_b32 s4, v254, 5
	s_waitcnt vmcnt(0) expcnt(0) lgkmcnt(0)
	s_nop 0
	v_mov_b32_e32 v0, s4
	ds_read_b32 v3, v0
	v_readlane_b32 s4, v254, 6
	s_waitcnt lgkmcnt(0)
	v_cmp_ne_u32_e32 vcc, 0, v3
	v_mov_b32_e32 v0, s4
	ds_read_b32 v2, v0
	s_cbranch_vccnz .LBB0_1040
	s_mov_b32 s4, 1
	s_branch .LBB0_1027

; #define LAS __attribute__((address_space(3)))
; __device__ __forceinline__ void sgu_unit(LAS unsigned char* lds, int tok0, const bf16_t* Gt, const bf16_t* U, const bf16_t* Wb, const float* bs, const float* lng, const float* lnb,
;                                          const i64* lnsum, const i64* lnsq, bf16_t* MIX, int wid, int lane_in) {
;     int lane = lane_in; asm volatile("" : "+v"(lane));
;     LAS float* MU = (LAS float*)(lds + SGU_TAB); LAS float* RS = MU + 128; LAS float* SS = RS + 128;
;     const int tid = wid * 64 + lane;
; #pragma unroll
;     for (int i = 0; i < 16; ++i) { const int P = ((i * 8 + wid) << 6) + lane, row = P >> 4, piece = (P & 15) ^ (row & 15);
;         __builtin_amdgcn_global_load_lds((const unsigned*)(Wb + (size_t)row * 128 + piece * 8), (LAS unsigned*)(lds + (i * 8 + wid) * 1024), 16, 0, 0); }
;     const int g = wid >> 1, e0 = 64 * (wid & 1), li = lane & 15, kq = lane >> 4;
;     float gg[4], gb[4]; u32x4 rawg[4][4];
; #pragma unroll
;     for (int et = 0; et < 4; ++et) { const int ch = g * 128 + e0 + 16 * (li >> 2) + 4 * et + (li & 3);
;         gg[et] = lng[ch]; gb[et] = lnb[ch];
; #pragma unroll
;         for (int c = 0; c < 4; ++c) rawg[c][et] = *(const u32x4*)(Gt + ((size_t)((tok0 + 32 * c + 8 * kq) >> 3) * 512 + ch) * 8); }
;     if (tid < 128) { const float sm = fx_get(lnsum + tok0 + tid) * (1.0f / DH); const float var = fx_get(lnsq + tok0 + tid) * (1.0f / DH) - sm * sm;
;         MU[tid] = sm; RS[tid] = __builtin_amdgcn_rsqf(fmaxf(var, 0.f) + EPS); }
;     asm volatile("s_waitcnt vmcnt(0)" ::: "memory");
;     __syncthreads();
;     f32x4 acc[4][8];
; #pragma unroll
;     for (int et = 0; et < 4; ++et)
; #pragma unroll
;         for (int tt = 0; tt < 8; ++tt) acc[et][tt] = (f32x4){0.f, 0.f, 0.f, 0.f};
;     const LAS unsigned char* wrow = lds + (size_t)(g * 128 + li) * 256;
;     ...
;     __syncthreads();
; #pragma unroll
;     for (int tt = 0; tt < 8; ++tt) {
;         const int t = 16 * tt + li; float tot = 0.f;
; #pragma unroll
;         for (int w8 = 0; w8 < 8; ++w8) tot += SS[w8 * 128 + t];
;         const float rstd = __builtin_amdgcn_rsqf(tot * (1.0f / DH) + EPS);
;         bf16_t* mp = MIX + (size_t)(tok0 + t) * DM + DH + g * 128 + e0 + 16 * kq;
; #pragma unroll
;         for (int eh = 0; eh < 2; ++eh) { const f32x4 va = acc[2 * eh][tt] * rstd, vb = acc[2 * eh + 1][tt] * rstd;
.Lsgu_early:
	v_readfirstlane_b32 s36, v210
	s_lshr_b32 s55, s36, 6
	s_mov_b64 s[46:47], s[94:95]
	s_branch .Lsgu_body
.LBB0_1109:
	v_readlane_b32 s4, v253, 54
	v_readlane_b32 s5, v253, 55
	s_mov_b64 s[46:47], s[94:95]
	v_mov_b32_e32 v0, 0x23084
	ds_read_b32 v0, v0
	s_waitcnt lgkmcnt(0)
	v_readfirstlane_b32 s6, v0
	s_nop 3
	s_cmp_lg_u32 s6, 0
	s_cbranch_scc1 .LBB0_1131
	s_andn2_b64 vcc, exec, s[4:5]
	s_cbranch_vccnz .LBB0_1131
.Lsgu_body:
	v_readlane_b32 s4, v252, 51
	v_readlane_b32 s5, v252, 52
	s_lshl_b64 s[4:5], s[4:5], 3
	s_add_u32 s4, s46, s4
	s_addc_u32 s5, s47, s5
	s_add_u32 s28, s46, 0x12400000
	s_addc_u32 s29, s47, 0
	v_readlane_b32 s6, v255, 4
	s_add_u32 s6, s46, s6
	s_addc_u32 s7, s47, 0
	s_add_u32 s30, s6, 0x15500000
	s_addc_u32 s31, s7, 0
	s_add_i32 s8, s55, 8
	s_add_i32 s9, s55, 16
	s_add_i32 s10, s55, 24
	s_add_i32 s11, s55, 32
	s_add_i32 s12, s55, 40
	s_add_i32 s13, s55, 48
	s_add_i32 s14, s55, 56
	s_add_i32 s15, s55, 64
	s_add_i32 s16, s55, 0x48
	s_add_i32 s17, s55, 0x50
	s_add_i32 s18, s55, 0x58
	s_add_i32 s19, s55, 0x60
	s_add_i32 s20, s55, 0x68
	s_add_i32 s21, s55, 0x70
	s_add_i32 s42, s55, 0x78
	s_and_b32 s6, s36, 0xffffffc0
	s_lshl_b32 s22, s55, 10
	s_lshl_b32 s7, s8, 6
	s_lshl_b32 s23, s8, 10
	s_lshl_b32 s8, s9, 6
	s_lshl_b32 s26, s9, 10
	s_lshl_b32 s9, s10, 6
	s_lshl_b32 s27, s10, 10
	s_lshl_b32 s10, s11, 6
	s_lshl_b32 s40, s11, 10
	s_lshl_b32 s11, s12, 6
	s_lshl_b32 s41, s12, 10
	s_lshl_b32 s12, s13, 6
	s_lshl_b32 s50, s13, 10
	s_lshl_b32 s13, s14, 6
	s_lshl_b32 s51, s14, 10
	s_lshl_b32 s14, s15, 6
	s_lshl_b32 s71, s15, 10
	s_lshl_b32 s15, s16, 6
	s_lshl_b32 s88, s16, 10
	s_lshl_b32 s16, s17, 6
	s_lshl_b32 s89, s17, 10
	s_lshl_b32 s17, s18, 6
	s_lshl_b32 s90, s18, 10
	s_lshl_b32 s18, s19, 6
	s_lshl_b32 s91, s19, 10
	s_lshl_b32 s19, s20, 6
	s_lshl_b32 s92, s20, 10
	s_lshl_b32 s20, s21, 6
	s_lshl_b32 s93, s21, 10
	s_lshl_b32 s21, s42, 6
	s_lshl_b32 s94, s42, 10
	s_and_b32 s48, s36, 64
	s_and_b32 s42, s36, 0xffffff80
	s_add_u32 s36, s4, 0x80000
	s_addc_u32 s52, s5, 0
	s_add_u32 s53, s4, 0x60000
	s_addc_u32 s54, s5, 0
	s_ashr_i32 s43, s42, 31
	s_lshl_b64 s[4:5], s[42:43], 1
	s_lshl_b32 s43, s48, 1
	s_add_u32 s4, s46, s4
	s_addc_u32 s5, s47, s5
	s_add_u32 s4, s4, s43
	s_addc_u32 s5, s5, 0
	s_add_u32 s46, s4, 0xe400000
	s_addc_u32 s47, s5, 0
	s_lshl_b32 s43, s55, 9
	s_add_i32 s43, s43, 0
	s_add_i32 s43, s43, 0x20400
	s_add_u32 s48, s4, 0x13400000
	s_addc_u32 s49, s5, 0
	s_add_i32 s55, s22, 0
	s_add_i32 s76, s23, 0
	s_add_i32 s77, s26, 0
	s_add_i32 s78, s27, 0
	s_add_i32 s79, s40, 0
	s_add_i32 s80, s41, 0
	s_add_i32 s81, s50, 0
	s_add_i32 s82, s51, 0
	s_add_i32 s83, s71, 0
	s_add_i32 s88, s88, 0
	s_add_i32 s89, s89, 0
	s_add_i32 s90, s90, 0
	s_add_i32 s91, s91, 0
	s_add_i32 s92, s92, 0
	s_add_i32 s93, s93, 0
	s_add_i32 s94, s94, 0
	v_readlane_b32 s95, v253, 63
	s_mov_b32 s96, s2
	s_cmp_lt_u32 s2, 0x80
	s_cbranch_scc1 .Lsgu_norm
	s_and_b32 s96, s2, 7
	s_lshl_b32 s96, s96, 3
	s_bfe_u32 s95, s2, 0x30004
	s_or_b32 s96, s96, s95
	s_lshl_b32 s96, s96, 1
	s_bfe_u32 s95, s2, 0x10003
	s_or_b32 s96, s96, s95
	s_lshl_b32 s95, s96, 7
	s_or_b32 s95, s95, 0x70
.Lsgu_norm:
	s_branch .LBB0_1112
.LBB0_1111:
	s_or_b64 exec, exec, s[50:51]
	v_lshl_add_u32 v0, v215, 2, 0
	v_add_u32_e32 v0, 0x20400, v0
	s_waitcnt lgkmcnt(0)
	s_barrier
	ds_read2st64_b32 v[30:31], v0 offset1:2
	v_readlane_b32 s4, v252, 31
	s_add_i32 s96, s96, s70
	s_add_i32 s95, s95, s4
	s_cmpk_gt_i32 s96, 0x7f
	s_waitcnt lgkmcnt(0)
	v_add_f32_e32 v30, 0, v30
	v_add_f32_e32 v32, v30, v31
	ds_read2st64_b32 v[30:31], v0 offset0:4 offset1:6
	s_waitcnt lgkmcnt(0)
	v_add_f32_e32 v30, v32, v30
	v_add_f32_e32 v32, v30, v31
	ds_read2st64_b32 v[30:31], v0 offset0:8 offset1:10
	s_waitcnt lgkmcnt(0)
	v_add_f32_e32 v30, v32, v30
	v_add_f32_e32 v32, v30, v31
	ds_read2st64_b32 v[30:31], v0 offset0:12 offset1:14
	s_waitcnt lgkmcnt(0)
	v_add_f32_e32 v30, v32, v30
	v_add_f32_e32 v30, v30, v31
	v_fmamk_f32 v30, v30, 0x3b000000, v213
	v_rsq_f32_e32 v32, v30
	v_lshlrev_b64 v[30:31], 11, v[190:191]
	v_lshl_add_u64 v[42:43], s[48:49], 0, v[30:31]
	v_lshlrev_b64 v[30:31], 1, v[188:189]
	v_lshl_add_u64 v[50:51], v[42:43], 0, v[30:31]
	v_pk_mul_f32 v[44:45], v[192:193], v[32:33] op_sel_hi:[1,0]
	v_pk_mul_f32 v[42:43], v[194:195], v[32:33] op_sel_hi:[1,0]
	v_pk_mul_f32 v[52:53], v[196:197], v[32:33] op_sel_hi:[1,0]
	v_pk_mul_f32 v[66:67], v[202:203], v[32:33] op_sel_hi:[1,0]
	v_cvt_pk_bf16_f32 v42, v42, v43
	v_cvt_pk_bf16_f32 v43, v44, v45
	s_nop 0
	v_cvt_pk_bf16_f32 v44, v66, v67
	v_cvt_pk_bf16_f32 v45, v52, v53
	global_store_dwordx4 v[50:51], v[42:45], off offset:1024
	v_pk_mul_f32 v[52:53], v[158:159], v[32:33] op_sel_hi:[1,0]
	s_nop 0
	v_pk_mul_f32 v[44:45], v[198:199], v[32:33] op_sel_hi:[1,0]
	v_pk_mul_f32 v[42:43], v[200:201], v[32:33] op_sel_hi:[1,0]
	v_pk_mul_f32 v[32:33], v[160:161], v[32:33] op_sel_hi:[1,0]
	v_cvt_pk_bf16_f32 v42, v42, v43
	v_cvt_pk_bf16_f32 v43, v44, v45
	s_nop 0
	v_cvt_pk_bf16_f32 v44, v32, v33
	v_cvt_pk_bf16_f32 v45, v52, v53
	ds_read2_b32 v[32:33], v0 offset0:16 offset1:144
	global_store_dwordx4 v[50:51], v[42:45], off offset:1040
	s_waitcnt lgkmcnt(0)
	v_add_f32_e32 v32, 0, v32
	v_add_f32_e32 v33, v32, v33
	v_add_u32_e32 v32, 64, v0
	ds_read2st64_b32 v[42:43], v32 offset0:4 offset1:6
	s_waitcnt lgkmcnt(0)
	v_add_f32_e32 v33, v33, v42
	v_add_f32_e32 v33, v33, v43
	ds_read2st64_b32 v[42:43], v32 offset0:8 offset1:10
	s_waitcnt lgkmcnt(0)
	v_add_f32_e32 v33, v33, v42
	v_add_f32_e32 v33, v33, v43
	ds_read2st64_b32 v[42:43], v32 offset0:12 offset1:14
	s_waitcnt lgkmcnt(0)
; __device__ __forceinline__ unsigned cvt_pk_bf16(float lo, float hi) { unsigned r; asm volatile("v_cvt_pk_bf16_f32 %0, %1, %2" : "=v"(r) : "v"(lo), "v"(hi)); return r; }
; __device__ __forceinline__ void sgu_unit(LAS unsigned char* lds, int tok0, const bf16_t* Gt, const bf16_t* U, const bf16_t* Wb, const float* bs, const float* lng, const float* lnb,
;                                          const i64* lnsum, const i64* lnsq, bf16_t* MIX, int wid, int lane_in) {
;     ...
; #pragma unroll
;     for (int tt = 0; tt < 8; ++tt) {
;         const int t = 16 * tt + li; float tot = 0.f;
; #pragma unroll
;         for (int w8 = 0; w8 < 8; ++w8) tot += SS[w8 * 128 + t];
;         const float rstd = __builtin_amdgcn_rsqf(tot * (1.0f / DH) + EPS);
;         bf16_t* mp = MIX + (size_t)(tok0 + t) * DM + DH + g * 128 + e0 + 16 * kq;
; #pragma unroll
;         for (int eh = 0; eh < 2; ++eh) { const f32x4 va = acc[2 * eh][tt] * rstd, vb = acc[2 * eh + 1][tt] * rstd;
;             u32x4 w; w.x = cvt_pk_bf16(va[0], va[1]); w.y = cvt_pk_bf16(va[2], va[3]); w.z = cvt_pk_bf16(vb[0], vb[1]); w.w = cvt_pk_bf16(vb[2], vb[3]); *(u32x4*)(mp + 8 * eh) = w; }
;     }
	v_add_f32_e32 v33, v33, v42
	v_add_f32_e32 v33, v33, v43
	v_fmamk_f32 v33, v33, 0x3b000000, v213
	v_rsq_f32_e32 v50, v33
	v_lshlrev_b64 v[42:43], 11, v[186:187]
	v_lshl_add_u64 v[42:43], s[48:49], 0, v[42:43]
	v_lshl_add_u64 v[52:53], v[42:43], 0, v[30:31]
	v_pk_mul_f32 v[42:43], v[156:157], v[50:51] op_sel_hi:[1,0]
	v_pk_mul_f32 v[44:45], v[154:155], v[50:51] op_sel_hi:[1,0]
	v_cvt_pk_bf16_f32 v42, v42, v43
	v_pk_mul_f32 v[66:67], v[146:147], v[50:51] op_sel_hi:[1,0]
	v_cvt_pk_bf16_f32 v43, v44, v45
	v_pk_mul_f32 v[68:69], v[148:149], v[50:51] op_sel_hi:[1,0]
	s_nop 0
	v_cvt_pk_bf16_f32 v44, v68, v69
	v_cvt_pk_bf16_f32 v45, v66, v67
	global_store_dwordx4 v[52:53], v[42:45], off offset:1024
	v_pk_mul_f32 v[66:67], v[134:135], v[50:51] op_sel_hi:[1,0]
	s_nop 0
	v_pk_mul_f32 v[42:43], v[144:145], v[50:51] op_sel_hi:[1,0]
	v_pk_mul_f32 v[44:45], v[142:143], v[50:51] op_sel_hi:[1,0]
	v_cvt_pk_bf16_f32 v42, v42, v43
	v_pk_mul_f32 v[50:51], v[136:137], v[50:51] op_sel_hi:[1,0]
	v_cvt_pk_bf16_f32 v43, v44, v45
	s_nop 0
	v_cvt_pk_bf16_f32 v44, v50, v51
	v_cvt_pk_bf16_f32 v45, v66, v67
	global_store_dwordx4 v[52:53], v[42:45], off offset:1040
	ds_read2_b32 v[42:43], v0 offset0:32 offset1:160
	s_waitcnt lgkmcnt(0)
	v_add_f32_e32 v33, 0, v42
	v_add_f32_e32 v44, v33, v43
	v_add_u32_e32 v33, 0x80, v0
	ds_read2st64_b32 v[42:43], v33 offset0:4 offset1:6
	s_waitcnt lgkmcnt(0)
	v_add_f32_e32 v42, v44, v42
	v_add_f32_e32 v44, v42, v43
	ds_read2st64_b32 v[42:43], v33 offset0:8 offset1:10
	s_waitcnt lgkmcnt(0)
	v_add_f32_e32 v42, v44, v42
	v_add_f32_e32 v44, v42, v43
	ds_read2st64_b32 v[42:43], v33 offset0:12 offset1:14
	s_waitcnt lgkmcnt(0)
	v_add_f32_e32 v42, v44, v42
	v_add_f32_e32 v42, v42, v43
	v_fmamk_f32 v42, v42, 0x3b000000, v213
	v_rsq_f32_e32 v50, v42
	v_lshlrev_b64 v[42:43], 11, v[184:185]
	v_lshl_add_u64 v[42:43], s[48:49], 0, v[42:43]
	v_lshl_add_u64 v[52:53], v[42:43], 0, v[30:31]
	v_pk_mul_f32 v[42:43], v[128:129], v[50:51] op_sel_hi:[1,0]
	v_pk_mul_f32 v[44:45], v[126:127], v[50:51] op_sel_hi:[1,0]
	v_cvt_pk_bf16_f32 v42, v42, v43
	v_pk_mul_f32 v[66:67], v[122:123], v[50:51] op_sel_hi:[1,0]
	v_cvt_pk_bf16_f32 v43, v44, v45
	v_pk_mul_f32 v[68:69], v[124:125], v[50:51] op_sel_hi:[1,0]
	s_nop 0
	v_cvt_pk_bf16_f32 v44, v68, v69
	v_cvt_pk_bf16_f32 v45, v66, v67
	global_store_dwordx4 v[52:53], v[42:45], off offset:1024
	v_pk_mul_f32 v[66:67], v[110:111], v[50:51] op_sel_hi:[1,0]
	s_nop 0
	v_pk_mul_f32 v[42:43], v[120:121], v[50:51] op_sel_hi:[1,0]
	v_pk_mul_f32 v[44:45], v[118:119], v[50:51] op_sel_hi:[1,0]
	v_cvt_pk_bf16_f32 v42, v42, v43
	v_pk_mul_f32 v[50:51], v[112:113], v[50:51] op_sel_hi:[1,0]
	v_cvt_pk_bf16_f32 v43, v44, v45
	s_nop 0
	v_cvt_pk_bf16_f32 v44, v50, v51
	v_cvt_pk_bf16_f32 v45, v66, v67
	global_store_dwordx4 v[52:53], v[42:45], off offset:1040
	ds_read2_b32 v[42:43], v0 offset0:48 offset1:176
	v_lshlrev_b64 v[50:51], 11, v[182:183]
	v_lshl_add_u64 v[50:51], s[48:49], 0, v[50:51]
	v_lshl_add_u64 v[66:67], v[50:51], 0, v[30:31]
	s_waitcnt lgkmcnt(0)
	v_add_f32_e32 v42, 0, v42
	v_add_f32_e32 v43, v42, v43
	v_add_u32_e32 v42, 0xc0, v0
	ds_read2st64_b32 v[44:45], v42 offset0:4 offset1:6
	s_waitcnt lgkmcnt(0)
	v_add_f32_e32 v43, v43, v44
	v_add_f32_e32 v43, v43, v45
	ds_read2st64_b32 v[44:45], v42 offset0:8 offset1:10
	s_waitcnt lgkmcnt(0)
	v_add_f32_e32 v43, v43, v44
	v_add_f32_e32 v43, v43, v45
	ds_read2st64_b32 v[44:45], v42 offset0:12 offset1:14
	s_waitcnt lgkmcnt(0)
	v_add_f32_e32 v43, v43, v44
	v_add_f32_e32 v43, v43, v45
	v_fmamk_f32 v43, v43, 0x3b000000, v213
	v_rsq_f32_e32 v44, v43
	s_nop 0
	v_pk_mul_f32 v[52:53], v[106:107], v[44:45] op_sel_hi:[1,0]
	v_pk_mul_f32 v[50:51], v[108:109], v[44:45] op_sel_hi:[1,0]
	v_pk_mul_f32 v[68:69], v[98:99], v[44:45] op_sel_hi:[1,0]
	v_pk_mul_f32 v[78:79], v[100:101], v[44:45] op_sel_hi:[1,0]
	v_cvt_pk_bf16_f32 v50, v50, v51
	v_cvt_pk_bf16_f32 v51, v52, v53
	s_nop 0
	v_cvt_pk_bf16_f32 v52, v78, v79
	v_cvt_pk_bf16_f32 v53, v68, v69
	global_store_dwordx4 v[66:67], v[50:53], off offset:1024
	v_pk_mul_f32 v[68:69], v[86:87], v[44:45] op_sel_hi:[1,0]
	s_nop 0
	v_pk_mul_f32 v[52:53], v[94:95], v[44:45] op_sel_hi:[1,0]
	v_pk_mul_f32 v[50:51], v[96:97], v[44:45] op_sel_hi:[1,0]
	v_pk_mul_f32 v[44:45], v[88:89], v[44:45] op_sel_hi:[1,0]
	v_cvt_pk_bf16_f32 v50, v50, v51
	v_cvt_pk_bf16_f32 v51, v52, v53
	s_nop 0
	v_cvt_pk_bf16_f32 v52, v44, v45
	v_cvt_pk_bf16_f32 v53, v68, v69
	ds_read2st64_b32 v[44:45], v0 offset0:1 offset1:3
	global_store_dwordx4 v[66:67], v[50:53], off offset:1040
	s_waitcnt lgkmcnt(0)
	v_add_f32_e32 v43, 0, v44
	v_add_f32_e32 v43, v43, v45
	ds_read2st64_b32 v[44:45], v0 offset0:5 offset1:7
	v_lshlrev_b64 v[50:51], 11, v[180:181]
	v_lshl_add_u64 v[50:51], s[48:49], 0, v[50:51]
	v_lshl_add_u64 v[66:67], v[50:51], 0, v[30:31]
	s_waitcnt lgkmcnt(0)
	v_add_f32_e32 v43, v43, v44
	v_add_f32_e32 v43, v43, v45
	ds_read2st64_b32 v[44:45], v0 offset0:9 offset1:11
	s_waitcnt lgkmcnt(0)
	v_add_f32_e32 v43, v43, v44
	v_add_f32_e32 v43, v43, v45
	ds_read2st64_b32 v[44:45], v0 offset0:13 offset1:15
	s_waitcnt lgkmcnt(0)
; __device__ __forceinline__ unsigned cvt_pk_bf16(float lo, float hi) { unsigned r; asm volatile("v_cvt_pk_bf16_f32 %0, %1, %2" : "=v"(r) : "v"(lo), "v"(hi)); return r; }
; __device__ __forceinline__ void sgu_unit(LAS unsigned char* lds, int tok0, const bf16_t* Gt, const bf16_t* U, const bf16_t* Wb, const float* bs, const float* lng, const float* lnb,
;                                          const i64* lnsum, const i64* lnsq, bf16_t* MIX, int wid, int lane_in) {
;     ...
; #pragma unroll
;     for (int tt = 0; tt < 8; ++tt) {
;         const int t = 16 * tt + li; float tot = 0.f;
; #pragma unroll
;         for (int w8 = 0; w8 < 8; ++w8) tot += SS[w8 * 128 + t];
;         const float rstd = __builtin_amdgcn_rsqf(tot * (1.0f / DH) + EPS);
;         bf16_t* mp = MIX + (size_t)(tok0 + t) * DM + DH + g * 128 + e0 + 16 * kq;
; #pragma unroll
;         for (int eh = 0; eh < 2; ++eh) { const f32x4 va = acc[2 * eh][tt] * rstd, vb = acc[2 * eh + 1][tt] * rstd;
;             u32x4 w; w.x = cvt_pk_bf16(va[0], va[1]); w.y = cvt_pk_bf16(va[2], va[3]); w.z = cvt_pk_bf16(vb[0], vb[1]); w.w = cvt_pk_bf16(vb[2], vb[3]); *(u32x4*)(mp + 8 * eh) = w; }
;     }
;     __syncthreads();
	v_add_f32_e32 v43, v43, v44
	v_add_f32_e32 v43, v43, v45
	v_fmamk_f32 v43, v43, 0x3b000000, v213
	v_rsq_f32_e32 v44, v43
	s_nop 0
	v_pk_mul_f32 v[52:53], v[82:83], v[44:45] op_sel_hi:[1,0]
	v_pk_mul_f32 v[50:51], v[84:85], v[44:45] op_sel_hi:[1,0]
	v_pk_mul_f32 v[68:69], v[74:75], v[44:45] op_sel_hi:[1,0]
	v_pk_mul_f32 v[74:75], v[76:77], v[44:45] op_sel_hi:[1,0]
	v_cvt_pk_bf16_f32 v50, v50, v51
	v_cvt_pk_bf16_f32 v51, v52, v53
	v_pk_mul_f32 v[62:63], v[62:63], v[44:45] op_sel_hi:[1,0]
	v_cvt_pk_bf16_f32 v52, v74, v75
	v_cvt_pk_bf16_f32 v53, v68, v69
	global_store_dwordx4 v[66:67], v[50:53], off offset:1024
	s_nop 1
	v_pk_mul_f32 v[52:53], v[70:71], v[44:45] op_sel_hi:[1,0]
	v_pk_mul_f32 v[50:51], v[72:73], v[44:45] op_sel_hi:[1,0]
	v_pk_mul_f32 v[44:45], v[64:65], v[44:45] op_sel_hi:[1,0]
	v_cvt_pk_bf16_f32 v50, v50, v51
	v_cvt_pk_bf16_f32 v51, v52, v53
	s_nop 0
	v_cvt_pk_bf16_f32 v52, v44, v45
	v_cvt_pk_bf16_f32 v53, v62, v63
	ds_read2_b32 v[44:45], v0 offset0:80 offset1:208
	global_store_dwordx4 v[66:67], v[50:53], off offset:1040
	s_waitcnt lgkmcnt(0)
	v_add_f32_e32 v43, 0, v44
	v_add_f32_e32 v43, v43, v45
	ds_read2st64_b32 v[44:45], v32 offset0:5 offset1:7
	s_waitcnt lgkmcnt(0)
	v_add_f32_e32 v43, v43, v44
	v_add_f32_e32 v43, v43, v45
	ds_read2st64_b32 v[44:45], v32 offset0:9 offset1:11
	s_waitcnt lgkmcnt(0)
	v_add_f32_e32 v43, v43, v44
	v_add_f32_e32 v43, v43, v45
	ds_read2st64_b32 v[44:45], v32 offset0:13 offset1:15
	s_waitcnt lgkmcnt(0)
	v_add_f32_e32 v32, v43, v44
	v_add_f32_e32 v32, v32, v45
	v_fmamk_f32 v32, v32, 0x3b000000, v213
	v_rsq_f32_e32 v32, v32
	v_lshlrev_b64 v[44:45], 11, v[178:179]
	v_lshl_add_u64 v[44:45], s[48:49], 0, v[44:45]
	v_lshl_add_u64 v[44:45], v[44:45], 0, v[30:31]
	v_pk_mul_f32 v[50:51], v[60:61], v[32:33] op_sel_hi:[1,0]
	v_pk_mul_f32 v[52:53], v[58:59], v[32:33] op_sel_hi:[1,0]
	v_cvt_pk_bf16_f32 v50, v50, v51
	v_pk_mul_f32 v[54:55], v[54:55], v[32:33] op_sel_hi:[1,0]
	v_cvt_pk_bf16_f32 v51, v52, v53
	v_pk_mul_f32 v[56:57], v[56:57], v[32:33] op_sel_hi:[1,0]
	v_pk_mul_f32 v[46:47], v[46:47], v[32:33] op_sel_hi:[1,0]
	v_cvt_pk_bf16_f32 v52, v56, v57
	v_cvt_pk_bf16_f32 v53, v54, v55
	global_store_dwordx4 v[44:45], v[50:53], off offset:1024
	v_pk_mul_f32 v[48:49], v[48:49], v[32:33] op_sel_hi:[1,0]
	v_pk_mul_f32 v[40:41], v[40:41], v[32:33] op_sel_hi:[1,0]
	v_pk_mul_f32 v[50:51], v[38:39], v[32:33] op_sel_hi:[1,0]
	v_cvt_pk_bf16_f32 v38, v48, v49
	v_cvt_pk_bf16_f32 v39, v46, v47
	v_cvt_pk_bf16_f32 v40, v40, v41
	s_nop 0
	v_cvt_pk_bf16_f32 v41, v50, v51
	global_store_dwordx4 v[44:45], v[38:41], off offset:1040
	ds_read2_b32 v[38:39], v0 offset0:96 offset1:224
	s_waitcnt lgkmcnt(0)
	v_add_f32_e32 v32, 0, v38
	v_add_f32_e32 v32, v32, v39
	ds_read2st64_b32 v[38:39], v33 offset0:5 offset1:7
	s_waitcnt lgkmcnt(0)
	v_add_f32_e32 v32, v32, v38
	v_add_f32_e32 v32, v32, v39
	ds_read2st64_b32 v[38:39], v33 offset0:9 offset1:11
	s_waitcnt lgkmcnt(0)
	v_add_f32_e32 v32, v32, v38
	v_add_f32_e32 v38, v32, v39
	ds_read2st64_b32 v[32:33], v33 offset0:13 offset1:15
	s_waitcnt lgkmcnt(0)
	v_add_f32_e32 v32, v38, v32
	v_add_f32_e32 v32, v32, v33
	v_fmamk_f32 v32, v32, 0x3b000000, v213
	v_rsq_f32_e32 v32, v32
	v_lshlrev_b64 v[38:39], 11, v[176:177]
	v_lshl_add_u64 v[38:39], s[48:49], 0, v[38:39]
	v_lshl_add_u64 v[38:39], v[38:39], 0, v[30:31]
	v_pk_mul_f32 v[34:35], v[34:35], v[32:33] op_sel_hi:[1,0]
	v_pk_mul_f32 v[36:37], v[36:37], v[32:33] op_sel_hi:[1,0]
	v_pk_mul_f32 v[40:41], v[26:27], v[32:33] op_sel_hi:[1,0]
	v_pk_mul_f32 v[28:29], v[28:29], v[32:33] op_sel_hi:[1,0]
	v_cvt_pk_bf16_f32 v26, v36, v37
	v_cvt_pk_bf16_f32 v27, v34, v35
	v_pk_mul_f32 v[22:23], v[22:23], v[32:33] op_sel_hi:[1,0]
	v_cvt_pk_bf16_f32 v28, v28, v29
	v_cvt_pk_bf16_f32 v29, v40, v41
	global_store_dwordx4 v[38:39], v[26:29], off offset:1024
	v_pk_mul_f32 v[24:25], v[24:25], v[32:33] op_sel_hi:[1,0]
	v_pk_mul_f32 v[20:21], v[20:21], v[32:33] op_sel_hi:[1,0]
	v_pk_mul_f32 v[26:27], v[18:19], v[32:33] op_sel_hi:[1,0]
	v_cvt_pk_bf16_f32 v18, v24, v25
	v_cvt_pk_bf16_f32 v19, v22, v23
	v_cvt_pk_bf16_f32 v20, v20, v21
	s_nop 0
	v_cvt_pk_bf16_f32 v21, v26, v27
	global_store_dwordx4 v[38:39], v[18:21], off offset:1040
	ds_read2_b32 v[18:19], v0 offset0:112 offset1:240
	s_waitcnt lgkmcnt(0)
	v_add_f32_e32 v0, 0, v18
	v_add_f32_e32 v0, v0, v19
	ds_read2st64_b32 v[18:19], v42 offset0:5 offset1:7
	s_waitcnt lgkmcnt(0)
	v_add_f32_e32 v0, v0, v18
	v_add_f32_e32 v0, v0, v19
	ds_read2st64_b32 v[18:19], v42 offset0:9 offset1:11
	s_waitcnt lgkmcnt(0)
	v_add_f32_e32 v0, v0, v18
	v_add_f32_e32 v0, v0, v19
	ds_read2st64_b32 v[18:19], v42 offset0:13 offset1:15
	s_waitcnt lgkmcnt(0)
	v_add_f32_e32 v0, v0, v18
	v_add_f32_e32 v0, v0, v19
	v_fmamk_f32 v0, v0, 0x3b000000, v213
	v_rsq_f32_e32 v0, v0
	v_lshlrev_b64 v[18:19], 11, v[174:175]
	v_lshl_add_u64 v[18:19], s[48:49], 0, v[18:19]
	v_lshl_add_u64 v[18:19], v[18:19], 0, v[30:31]
	v_pk_mul_f32 v[14:15], v[14:15], v[0:1] op_sel_hi:[1,0]
	v_pk_mul_f32 v[16:17], v[16:17], v[0:1] op_sel_hi:[1,0]
	v_pk_mul_f32 v[20:21], v[10:11], v[0:1] op_sel_hi:[1,0]
	v_pk_mul_f32 v[12:13], v[12:13], v[0:1] op_sel_hi:[1,0]
	v_cvt_pk_bf16_f32 v10, v16, v17
	v_cvt_pk_bf16_f32 v11, v14, v15
	v_pk_mul_f32 v[4:5], v[4:5], v[0:1] op_sel_hi:[1,0]
	v_cvt_pk_bf16_f32 v12, v12, v13
	v_cvt_pk_bf16_f32 v13, v20, v21
	global_store_dwordx4 v[18:19], v[10:13], off offset:1024
	v_pk_mul_f32 v[6:7], v[6:7], v[0:1] op_sel_hi:[1,0]
	v_pk_mul_f32 v[8:9], v[8:9], v[0:1] op_sel_hi:[1,0]
	v_pk_mul_f32 v[10:11], v[2:3], v[0:1] op_sel_hi:[1,0]
	v_cvt_pk_bf16_f32 v2, v8, v9
	v_cvt_pk_bf16_f32 v3, v6, v7
	v_cvt_pk_bf16_f32 v4, v4, v5
	s_nop 0
	v_cvt_pk_bf16_f32 v5, v10, v11
	global_store_dwordx4 v[18:19], v[2:5], off offset:1040
	s_barrier
	s_cbranch_scc1 .LBB0_1130

; template <class T> __device__ __forceinline__ T* as_global(T* p) { return (T*)(GAS T*)p; }
; #define SEAM(k) do { if ((k) + 1 < hi) { if ((k) == 0) grid.sync(); else { xcd_barrier(bar); if (DUP & 4) xcd_barrier(bar); } } } while (0)
; #define SEAM(k) do { } while (0)
; #define WSBASE() GAS unsigned char* wsg_ = (GAS unsigned char*)a.ws; asm volatile("" : "+s"(wsg_)); unsigned char* ws = (unsigned char*)wsg_; i64* stats = (i64*)(ws + WS_STATS); i64* st = stats + (size_t)(6 * l) * MTOK; unsigned char* wl = ws + WS_W + (size_t)l * WL_STRIDE; (void)st; (void)wl
; __global__ void __launch_bounds__(NWAVES * 64, 2) fwd_kernel(Args a) {
;     ...
;                 if (!(SKIP & 8)) { WSBASE();
;                   for (int u = cu; u < MTOK / 128; u += G) for (int rp = 0; rp < ((DUP & 2) ? 2 : 1); ++rp)
;                     sgu_unit(lds, u * 128, (const bf16_t*)(ws + WS_GT), (const bf16_t*)(ws + WS_U), (const bf16_t*)(ws + WS_SGUW) + (size_t)l * 4 * 16384, as_global(a.in[10]) + l * 512, as_global(a.in[7]) + l * DH, as_global(a.in[8]) + l * DH,
;                              st + 3 * MTOK, st + 4 * MTOK, (bf16_t*)(ws + WS_MIX), wave, lane); }
;                 SEAM(pb + 3);
.LBB0_1130:
	s_load_dwordx2 s[94:95], s[0:1], 0xa0
	v_mov_b32_e32 v0, 0x23084
	ds_read_b32 v0, v0
	s_waitcnt lgkmcnt(0)
	v_readfirstlane_b32 s4, v0
	s_nop 3
	s_cmp_eq_u32 s4, 0
	s_cbranch_scc1 .Lsgu_exit_norm
	v_readlane_b32 s46, v255, 10
	v_readlane_b32 s47, v255, 11
	v_readlane_b32 s48, v255, 12
	v_readlane_b32 s49, v255, 13
	v_readlane_b32 s50, v255, 14
	v_readlane_b32 s51, v255, 15
	v_readlane_b32 s52, v255, 16
	v_readlane_b32 s53, v255, 17
	s_branch .Lin_seam
.Lsgu_exit_norm:
.LBB0_1131:
	v_readlane_b32 s4, v254, 58
	v_readlane_b32 s5, v254, 59
	s_and_b64 vcc, exec, s[4:5]
	s_cbranch_vccz .LBB0_1185
	s_waitcnt vmcnt(0)
	s_waitcnt vmcnt(0) lgkmcnt(0)
	s_barrier
	s_mov_b64 s[28:29], exec
	v_readlane_b32 s4, v254, 7
	v_readlane_b32 s5, v254, 8
	s_and_b64 s[4:5], s[28:29], s[4:5]
	s_mov_b64 exec, s[4:5]
	s_cbranch_execz .LBB0_1184
	v_readlane_b32 s4, v254, 5
	s_waitcnt vmcnt(0) expcnt(0) lgkmcnt(0)
	s_nop 0
	v_mov_b32_e32 v0, s4
	ds_read_b32 v3, v0
	v_readlane_b32 s4, v254, 6
	s_waitcnt lgkmcnt(0)
	v_cmp_ne_u32_e32 vcc, 0, v3
	v_mov_b32_e32 v0, s4
	ds_read_b32 v2, v0
	s_cbranch_vccnz .LBB0_1148
	s_mov_b32 s4, 1
	s_branch .LBB0_1136
